# w_in K-loop: the 16 independent MFMAs of each phase reordered so four consecutive ones share the B-fragment operand
# baseline (speedup 1.0000x reference)
; #define PG8_STAGE(bufoff, gbase, voff) do { _Pragma("unroll") for (int _i = 0; _i < 2; ++_i) \
;         __builtin_amdgcn_global_load_lds((const unsigned*)((const char*)(gbase) + (voff)[_i]), (LAS unsigned*)(lds + (bufoff) + ldsw + _i * 8192), 16, 0, 0); } while (0)
; #define PG8_LDA(dst, b, h) do { _Pragma("unroll") for (int m = 0; m < 4; ++m) _Pragma("unroll") for (int k = 0; k < 2; ++k) dst[m][k] = *(const LAS bf16x8*)(lds + PG8_SA(b, h) + aoff + m * 2048 + k * 1024); } while (0)
; #define PG8_LDB(dst, b, h) do { _Pragma("unroll") for (int n = 0; n < 2; ++n) _Pragma("unroll") for (int k = 0; k < 2; ++k) dst[n][k] = *(const LAS bf16x8*)(lds + PG8_SB(b, h) + boff + n * 2048 + k * 1024); } while (0)
; #define PG8_MMA(ai, bj, At, Bt) do { __builtin_amdgcn_s_setprio(1); _Pragma("unroll") for (int m = 0; m < 4; ++m) _Pragma("unroll") for (int n = 0; n < 2; ++n) _Pragma("unroll") for (int k = 0; k < 2; ++k) \
;         acc[ai][bj][m][n] = __builtin_amdgcn_mfma_f32_16x16x32_bf16(Bt[n][k], At[m][k], acc[ai][bj][m][n], 0, 0, 0); __builtin_amdgcn_s_setprio(0); } while (0)
; #define PG8_WAIT_V(n) asm volatile("s_waitcnt vmcnt(" #n ")" ::: "memory")
; #define PG8_WAIT_L(n) asm volatile("s_waitcnt lgkmcnt(" #n ")" ::: "memory")
; #define PG8_BAR __builtin_amdgcn_s_barrier()
; template <class Epi, class Sched>
; __device__ __forceinline__ void gemm_phase(LAS unsigned char* lds, const Gemm g, const Sched& S, const Epi& E) {
;     ...
;             const bool last = (t == nt - 2);
;             const char* a1 = cA + (size_t)(t + 1) * kstep;
;             const char* a2 = last ? nA : cA + (size_t)(t + 2) * kstep; const char* b2 = last ? nB : cB + (size_t)(t + 2) * kstep;
;             const char* a3 = a2 + kstep; const char* b3 = b2 + kstep;
;             PG8_LDB(B0, 0, 0); PG8_SCHED; PG8_LDA(At, 0, 0); PG8_STAGE(PG8_SA(1, 1), a1 + hstep, voffA);
;             PG8_WAIT_L(8); PG8_BAR; PG8_WAIT_L(0); PG8_MMA(0, 0, At, B0); PG8_BAR; PG8_SCHED;
;             PG8_LDB(B1, 0, 1); PG8_STAGE(PG8_SB(0, 0), b2, voffB);
;             PG8_BAR; PG8_WAIT_L(0); PG8_MMA(0, 1, At, B1); PG8_BAR;
;             PG8_LDA(At, 0, 1); PG8_STAGE(PG8_SA(0, 0), a2, voffA);
;             PG8_BAR; PG8_WAIT_L(0); PG8_MMA(1, 0, At, B0); PG8_BAR; PG8_SCHED;
;             PG8_STAGE(PG8_SB(0, 1), b2 + hstep, voffB);
;             PG8_WAIT_V(6); PG8_BAR; PG8_MMA(1, 1, At, B1); PG8_BAR;
.LBB0_852:
	s_add_u32 s18, s16, 0xfff80080
	s_addc_u32 s19, s17, -1
	s_add_i32 s39, 0, 0x10000
	v_add_u32_e32 v154, s39, v139
	ds_read_b128 v[142:145], v154
	ds_read_b128 v[146:149], v154 offset:1024
	ds_read_b128 v[150:153], v154 offset:2048
	ds_read_b128 v[154:157], v154 offset:3072
	s_cmp_eq_u32 s38, 28
	s_cselect_b32 s21, s11, s19
	s_cselect_b32 s20, s34, s18
	s_cselect_b32 s19, s9, s37
	s_cselect_b32 s18, s35, s36
	v_lshl_add_u64 v[174:175], s[16:17], 0, v[136:137]
	s_add_i32 m0, s7, 0xc000
	ds_read_b128 v[158:161], v141
	ds_read_b128 v[162:165], v141 offset:1024
	ds_read_b128 v[166:169], v141 offset:2048
	ds_read_b128 v[170:173], v141 offset:3072
	ds_read_b128 v[192:195], v141 offset:4096
	ds_read_b128 v[196:199], v141 offset:5120
	ds_read_b128 v[200:203], v141 offset:6144
	ds_read_b128 v[204:207], v141 offset:7168
	global_load_lds_dwordx4 v[174:175], off
	v_lshl_add_u64 v[174:175], s[16:17], 0, v[134:135]
	s_add_i32 m0, s7, 0xe000
	s_nop 0
	global_load_lds_dwordx4 v[174:175], off
	s_waitcnt lgkmcnt(8)
	s_barrier
	s_waitcnt lgkmcnt(0)
	s_setprio 1
	s_waitcnt lgkmcnt(0)
	v_mfma_f32_16x16x32_bf16 v[124:127], v[142:145], v[158:161], v[124:127]
	v_mfma_f32_16x16x32_bf16 v[116:119], v[142:145], v[166:169], v[116:119]
	v_mfma_f32_16x16x32_bf16 v[100:103], v[142:145], v[192:195], v[100:103]
	v_mfma_f32_16x16x32_bf16 v[84:87], v[142:145], v[200:203], v[84:87]
	v_mfma_f32_16x16x32_bf16 v[120:123], v[150:153], v[158:161], v[120:123]
	v_mfma_f32_16x16x32_bf16 v[112:115], v[150:153], v[166:169], v[112:115]
	v_mfma_f32_16x16x32_bf16 v[96:99], v[150:153], v[192:195], v[96:99]
	v_mfma_f32_16x16x32_bf16 v[80:83], v[150:153], v[200:203], v[80:83]
	v_mfma_f32_16x16x32_bf16 v[124:127], v[146:149], v[162:165], v[124:127]
	v_mfma_f32_16x16x32_bf16 v[116:119], v[146:149], v[170:173], v[116:119]
	v_mfma_f32_16x16x32_bf16 v[100:103], v[146:149], v[196:199], v[100:103]
	v_mfma_f32_16x16x32_bf16 v[84:87], v[146:149], v[204:207], v[84:87]
	v_mfma_f32_16x16x32_bf16 v[120:123], v[154:157], v[162:165], v[120:123]
	v_mfma_f32_16x16x32_bf16 v[112:115], v[154:157], v[170:173], v[112:115]
	v_mfma_f32_16x16x32_bf16 v[96:99], v[154:157], v[196:199], v[96:99]
	v_mfma_f32_16x16x32_bf16 v[80:83], v[154:157], v[204:207], v[80:83]
	s_setprio 0
	s_barrier
	s_add_i32 s42, 0, 0x14000
	v_add_u32_e32 v174, s42, v139
	s_add_i32 s39, s39, s23
	ds_read_b128 v[208:211], v174
	ds_read_b128 v[212:215], v174 offset:1024
	ds_read_b128 v[216:219], v174 offset:2048
	ds_read_b128 v[220:223], v174 offset:3072
	v_lshl_add_u64 v[174:175], s[18:19], 0, v[176:177]
	s_mov_b32 m0, s39
	v_lshl_add_u64 v[224:225], s[18:19], 0, v[128:129]
	global_load_lds_dwordx4 v[174:175], off
	s_add_i32 m0, s39, 0x2000
	s_nop 0
	global_load_lds_dwordx4 v[224:225], off
	s_barrier
	s_waitcnt lgkmcnt(0)
	s_setprio 1
	s_waitcnt lgkmcnt(0)
	v_mfma_f32_16x16x32_bf16 v[108:111], v[208:211], v[158:161], v[108:111]
	v_mfma_f32_16x16x32_bf16 v[92:95], v[208:211], v[166:169], v[92:95]
	v_mfma_f32_16x16x32_bf16 v[76:79], v[208:211], v[192:195], v[76:79]
	v_mfma_f32_16x16x32_bf16 v[68:71], v[208:211], v[200:203], v[68:71]
	v_mfma_f32_16x16x32_bf16 v[104:107], v[216:219], v[158:161], v[104:107]
	v_mfma_f32_16x16x32_bf16 v[88:91], v[216:219], v[166:169], v[88:91]
	v_mfma_f32_16x16x32_bf16 v[72:75], v[216:219], v[192:195], v[72:75]
	v_mfma_f32_16x16x32_bf16 v[64:67], v[216:219], v[200:203], v[64:67]
	v_mfma_f32_16x16x32_bf16 v[108:111], v[212:215], v[162:165], v[108:111]
	v_mfma_f32_16x16x32_bf16 v[92:95], v[212:215], v[170:173], v[92:95]
	v_mfma_f32_16x16x32_bf16 v[76:79], v[212:215], v[196:199], v[76:79]
	v_mfma_f32_16x16x32_bf16 v[68:71], v[212:215], v[204:207], v[68:71]
	v_mfma_f32_16x16x32_bf16 v[104:107], v[220:223], v[162:165], v[104:107]
	v_mfma_f32_16x16x32_bf16 v[88:91], v[220:223], v[170:173], v[88:91]
	v_mfma_f32_16x16x32_bf16 v[72:75], v[220:223], v[196:199], v[72:75]
	v_mfma_f32_16x16x32_bf16 v[64:67], v[220:223], v[204:207], v[64:67]
	s_setprio 0
	s_mov_b32 m0, s7
	v_lshl_add_u64 v[226:227], s[20:21], 0, v[132:133]
	s_barrier
	ds_read_b128 v[158:161], v141 offset:16384
	ds_read_b128 v[162:165], v141 offset:17408
	ds_read_b128 v[166:169], v141 offset:18432
	ds_read_b128 v[170:173], v141 offset:19456
	ds_read_b128 v[192:195], v141 offset:20480
	ds_read_b128 v[196:199], v141 offset:21504
	ds_read_b128 v[200:203], v141 offset:22528
	ds_read_b128 v[204:207], v141 offset:23552
	global_load_lds_dwordx4 v[226:227], off
	v_lshl_add_u64 v[228:229], s[20:21], 0, v[130:131]
	s_mov_b32 m0, s25
	s_nop 0
	global_load_lds_dwordx4 v[228:229], off
	s_barrier
	s_waitcnt lgkmcnt(0)
	s_setprio 1
	s_waitcnt lgkmcnt(0)
	v_mfma_f32_16x16x32_bf16 v[60:63], v[142:145], v[158:161], v[60:63]
	v_mfma_f32_16x16x32_bf16 v[52:55], v[142:145], v[166:169], v[52:55]
	v_mfma_f32_16x16x32_bf16 v[36:39], v[142:145], v[192:195], v[36:39]
	v_mfma_f32_16x16x32_bf16 v[20:23], v[142:145], v[200:203], v[20:23]
	v_mfma_f32_16x16x32_bf16 v[56:59], v[150:153], v[158:161], v[56:59]
	v_mfma_f32_16x16x32_bf16 v[48:51], v[150:153], v[166:169], v[48:51]
	v_mfma_f32_16x16x32_bf16 v[32:35], v[150:153], v[192:195], v[32:35]
	v_mfma_f32_16x16x32_bf16 v[16:19], v[150:153], v[200:203], v[16:19]
	v_mfma_f32_16x16x32_bf16 v[60:63], v[146:149], v[162:165], v[60:63]
	v_mfma_f32_16x16x32_bf16 v[52:55], v[146:149], v[170:173], v[52:55]
	v_mfma_f32_16x16x32_bf16 v[36:39], v[146:149], v[196:199], v[36:39]
	v_mfma_f32_16x16x32_bf16 v[20:23], v[146:149], v[204:207], v[20:23]
	v_mfma_f32_16x16x32_bf16 v[56:59], v[154:157], v[162:165], v[56:59]
	v_mfma_f32_16x16x32_bf16 v[48:51], v[154:157], v[170:173], v[48:51]
	v_mfma_f32_16x16x32_bf16 v[32:35], v[154:157], v[196:199], v[32:35]
	v_mfma_f32_16x16x32_bf16 v[16:19], v[154:157], v[204:207], v[16:19]
	s_setprio 0
	s_barrier
; #define PG8_STAGE(bufoff, gbase, voff) do { _Pragma("unroll") for (int _i = 0; _i < 2; ++_i) \
;         __builtin_amdgcn_global_load_lds((const unsigned*)((const char*)(gbase) + (voff)[_i]), (LAS unsigned*)(lds + (bufoff) + ldsw + _i * 8192), 16, 0, 0); } while (0)
; #define PG8_LDA(dst, b, h) do { _Pragma("unroll") for (int m = 0; m < 4; ++m) _Pragma("unroll") for (int k = 0; k < 2; ++k) dst[m][k] = *(const LAS bf16x8*)(lds + PG8_SA(b, h) + aoff + m * 2048 + k * 1024); } while (0)
; #define PG8_LDB(dst, b, h) do { _Pragma("unroll") for (int n = 0; n < 2; ++n) _Pragma("unroll") for (int k = 0; k < 2; ++k) dst[n][k] = *(const LAS bf16x8*)(lds + PG8_SB(b, h) + boff + n * 2048 + k * 1024); } while (0)
; #define PG8_MMA(ai, bj, At, Bt) do { __builtin_amdgcn_s_setprio(1); _Pragma("unroll") for (int m = 0; m < 4; ++m) _Pragma("unroll") for (int n = 0; n < 2; ++n) _Pragma("unroll") for (int k = 0; k < 2; ++k) \
;         acc[ai][bj][m][n] = __builtin_amdgcn_mfma_f32_16x16x32_bf16(Bt[n][k], At[m][k], acc[ai][bj][m][n], 0, 0, 0); __builtin_amdgcn_s_setprio(0); } while (0)
; #define PG8_WAIT_V(n) asm volatile("s_waitcnt vmcnt(" #n ")" ::: "memory")
; #define PG8_WAIT_L(n) asm volatile("s_waitcnt lgkmcnt(" #n ")" ::: "memory")
; #define PG8_BAR __builtin_amdgcn_s_barrier()
; #define PG8_SCHED __builtin_amdgcn_sched_barrier(0)
; template <class Epi, class Sched>
; __device__ __forceinline__ void gemm_phase(LAS unsigned char* lds, const Gemm g, const Sched& S, const Epi& E) {
;     ...
;             PG8_STAGE(PG8_SB(0, 1), b2 + hstep, voffB);
;             PG8_WAIT_V(6); PG8_BAR; PG8_MMA(1, 1, At, B1); PG8_BAR;
;             PG8_LDB(B0, 1, 0); PG8_SCHED; PG8_LDA(At, 1, 0); PG8_STAGE(PG8_SA(0, 1), a2 + hstep, voffA);
;             PG8_WAIT_L(8); PG8_BAR; PG8_WAIT_L(0); PG8_MMA(0, 0, At, B0); PG8_BAR; PG8_SCHED;
;             PG8_LDB(B1, 1, 1); PG8_STAGE(PG8_SB(1, 0), b3, voffB);
;             PG8_BAR; PG8_WAIT_L(0); PG8_MMA(0, 1, At, B1); PG8_BAR;
;             PG8_LDA(At, 1, 1); PG8_STAGE(PG8_SA(1, 0), a3, voffA);
;             PG8_BAR; PG8_WAIT_L(0); PG8_MMA(1, 0, At, B0); PG8_BAR; PG8_SCHED;
	s_add_u32 s40, s18, 0x80000
	s_addc_u32 s41, s19, 0
	s_add_i32 s39, s42, s23
	v_lshl_add_u64 v[142:143], s[40:41], 0, v[176:177]
	s_mov_b32 m0, s39
	s_nop 0
	global_load_lds_dwordx4 v[142:143], off
	v_lshl_add_u64 v[142:143], s[40:41], 0, v[128:129]
	s_add_i32 m0, s39, 0x2000
	s_nop 0
	global_load_lds_dwordx4 v[142:143], off
	s_waitcnt vmcnt(6)
	s_barrier
	s_setprio 1
	v_mfma_f32_16x16x32_bf16 v[44:47], v[208:211], v[158:161], v[44:47]
	v_mfma_f32_16x16x32_bf16 v[28:31], v[208:211], v[166:169], v[28:31]
	v_mfma_f32_16x16x32_bf16 v[12:15], v[208:211], v[192:195], v[12:15]
	v_mfma_f32_16x16x32_bf16 v[4:7], v[208:211], v[200:203], v[4:7]
	v_mfma_f32_16x16x32_bf16 v[40:43], v[216:219], v[158:161], v[40:43]
	v_mfma_f32_16x16x32_bf16 v[24:27], v[216:219], v[166:169], v[24:27]
	v_mfma_f32_16x16x32_bf16 v[8:11], v[216:219], v[192:195], v[8:11]
	v_mfma_f32_16x16x32_bf16 v[0:3], v[216:219], v[200:203], v[0:3]
	v_mfma_f32_16x16x32_bf16 v[44:47], v[212:215], v[162:165], v[44:47]
	v_mfma_f32_16x16x32_bf16 v[28:31], v[212:215], v[170:173], v[28:31]
	v_mfma_f32_16x16x32_bf16 v[12:15], v[212:215], v[196:199], v[12:15]
	v_mfma_f32_16x16x32_bf16 v[4:7], v[212:215], v[204:207], v[4:7]
	v_mfma_f32_16x16x32_bf16 v[40:43], v[220:223], v[162:165], v[40:43]
	v_mfma_f32_16x16x32_bf16 v[24:27], v[220:223], v[170:173], v[24:27]
	v_mfma_f32_16x16x32_bf16 v[8:11], v[220:223], v[196:199], v[8:11]
	v_mfma_f32_16x16x32_bf16 v[0:3], v[220:223], v[204:207], v[0:3]
	s_setprio 0
	s_add_i32 s39, 0, 0x18000
	v_add_u32_e32 v154, s39, v139
	s_barrier
	ds_read_b128 v[142:145], v154
	ds_read_b128 v[146:149], v154 offset:1024
	ds_read_b128 v[150:153], v154 offset:2048
	ds_read_b128 v[154:157], v154 offset:3072
	s_add_u32 s20, s20, 0x80000
	s_addc_u32 s21, s21, 0
	s_mov_b32 m0, s26
	v_lshl_add_u64 v[208:209], s[20:21], 0, v[132:133]
	ds_read_b128 v[158:161], v141 offset:32768
	ds_read_b128 v[162:165], v141 offset:33792
	ds_read_b128 v[166:169], v141 offset:34816
	ds_read_b128 v[170:173], v141 offset:35840
	ds_read_b128 v[192:195], v141 offset:36864
	ds_read_b128 v[196:199], v141 offset:37888
	ds_read_b128 v[200:203], v141 offset:38912
	ds_read_b128 v[204:207], v141 offset:39936
	global_load_lds_dwordx4 v[208:209], off
	v_lshl_add_u64 v[208:209], s[20:21], 0, v[130:131]
	s_mov_b32 m0, s27
	s_nop 0
	global_load_lds_dwordx4 v[208:209], off
	s_waitcnt lgkmcnt(8)
	s_barrier
	s_waitcnt lgkmcnt(0)
	s_setprio 1
	s_waitcnt lgkmcnt(0)
	v_mfma_f32_16x16x32_bf16 v[124:127], v[142:145], v[158:161], v[124:127]
	v_mfma_f32_16x16x32_bf16 v[116:119], v[142:145], v[166:169], v[116:119]
	v_mfma_f32_16x16x32_bf16 v[100:103], v[142:145], v[192:195], v[100:103]
	v_mfma_f32_16x16x32_bf16 v[84:87], v[142:145], v[200:203], v[84:87]
	v_mfma_f32_16x16x32_bf16 v[120:123], v[150:153], v[158:161], v[120:123]
	v_mfma_f32_16x16x32_bf16 v[112:115], v[150:153], v[166:169], v[112:115]
	v_mfma_f32_16x16x32_bf16 v[96:99], v[150:153], v[192:195], v[96:99]
	v_mfma_f32_16x16x32_bf16 v[80:83], v[150:153], v[200:203], v[80:83]
	v_mfma_f32_16x16x32_bf16 v[124:127], v[146:149], v[162:165], v[124:127]
	v_mfma_f32_16x16x32_bf16 v[116:119], v[146:149], v[170:173], v[116:119]
	v_mfma_f32_16x16x32_bf16 v[100:103], v[146:149], v[196:199], v[100:103]
	v_mfma_f32_16x16x32_bf16 v[84:87], v[146:149], v[204:207], v[84:87]
	v_mfma_f32_16x16x32_bf16 v[120:123], v[154:157], v[162:165], v[120:123]
	v_mfma_f32_16x16x32_bf16 v[112:115], v[154:157], v[170:173], v[112:115]
	v_mfma_f32_16x16x32_bf16 v[96:99], v[154:157], v[196:199], v[96:99]
	v_mfma_f32_16x16x32_bf16 v[80:83], v[154:157], v[204:207], v[80:83]
	s_setprio 0
	s_barrier
	s_add_i32 s20, 0, 0x1c000
	s_add_i32 s21, s39, s23
	v_add_u32_e32 v191, s20, v139
	v_lshl_add_u64 v[174:175], v[174:175], 0, s[82:83]
	s_mov_b32 m0, s21
	ds_read_b128 v[208:211], v191
	ds_read_b128 v[212:215], v191 offset:1024
	ds_read_b128 v[216:219], v191 offset:2048
	ds_read_b128 v[220:223], v191 offset:3072
	global_load_lds_dwordx4 v[174:175], off
	v_lshl_add_u64 v[174:175], v[224:225], 0, s[82:83]
	s_add_i32 m0, s21, 0x2000
	s_nop 0
	global_load_lds_dwordx4 v[174:175], off
	s_barrier
	s_waitcnt lgkmcnt(0)
	s_setprio 1
	s_waitcnt lgkmcnt(0)
	v_mfma_f32_16x16x32_bf16 v[108:111], v[208:211], v[158:161], v[108:111]
	v_mfma_f32_16x16x32_bf16 v[92:95], v[208:211], v[166:169], v[92:95]
	v_mfma_f32_16x16x32_bf16 v[76:79], v[208:211], v[192:195], v[76:79]
	v_mfma_f32_16x16x32_bf16 v[68:71], v[208:211], v[200:203], v[68:71]
	v_mfma_f32_16x16x32_bf16 v[104:107], v[216:219], v[158:161], v[104:107]
	v_mfma_f32_16x16x32_bf16 v[88:91], v[216:219], v[166:169], v[88:91]
	v_mfma_f32_16x16x32_bf16 v[72:75], v[216:219], v[192:195], v[72:75]
	v_mfma_f32_16x16x32_bf16 v[64:67], v[216:219], v[200:203], v[64:67]
	v_mfma_f32_16x16x32_bf16 v[108:111], v[212:215], v[162:165], v[108:111]
	v_mfma_f32_16x16x32_bf16 v[92:95], v[212:215], v[170:173], v[92:95]
	v_mfma_f32_16x16x32_bf16 v[76:79], v[212:215], v[196:199], v[76:79]
	v_mfma_f32_16x16x32_bf16 v[68:71], v[212:215], v[204:207], v[68:71]
	v_mfma_f32_16x16x32_bf16 v[104:107], v[220:223], v[162:165], v[104:107]
	v_mfma_f32_16x16x32_bf16 v[88:91], v[220:223], v[170:173], v[88:91]
	v_mfma_f32_16x16x32_bf16 v[72:75], v[220:223], v[196:199], v[72:75]
	v_mfma_f32_16x16x32_bf16 v[64:67], v[220:223], v[204:207], v[64:67]
	s_setprio 0
	s_mov_b32 m0, s28
	v_lshl_add_u64 v[174:175], v[226:227], 0, s[82:83]
	s_barrier
	ds_read_b128 v[158:161], v141 offset:49152
	ds_read_b128 v[162:165], v141 offset:50176
	ds_read_b128 v[166:169], v141 offset:51200
	ds_read_b128 v[170:173], v141 offset:52224
	ds_read_b128 v[192:195], v141 offset:53248
	ds_read_b128 v[196:199], v141 offset:54272
	ds_read_b128 v[200:203], v141 offset:55296
	ds_read_b128 v[204:207], v141 offset:56320
	global_load_lds_dwordx4 v[174:175], off
	v_lshl_add_u64 v[174:175], v[228:229], 0, s[82:83]
	s_mov_b32 m0, s29
	s_nop 0
	global_load_lds_dwordx4 v[174:175], off
	s_barrier
; #define PG8_STAGE(bufoff, gbase, voff) do { _Pragma("unroll") for (int _i = 0; _i < 2; ++_i) \
;         __builtin_amdgcn_global_load_lds((const unsigned*)((const char*)(gbase) + (voff)[_i]), (LAS unsigned*)(lds + (bufoff) + ldsw + _i * 8192), 16, 0, 0); } while (0)
; #define PG8_MMA(ai, bj, At, Bt) do { __builtin_amdgcn_s_setprio(1); _Pragma("unroll") for (int m = 0; m < 4; ++m) _Pragma("unroll") for (int n = 0; n < 2; ++n) _Pragma("unroll") for (int k = 0; k < 2; ++k) \
;         acc[ai][bj][m][n] = __builtin_amdgcn_mfma_f32_16x16x32_bf16(Bt[n][k], At[m][k], acc[ai][bj][m][n], 0, 0, 0); __builtin_amdgcn_s_setprio(0); } while (0)
; #define PG8_WAIT_V(n) asm volatile("s_waitcnt vmcnt(" #n ")" ::: "memory")
; #define PG8_WAIT_L(n) asm volatile("s_waitcnt lgkmcnt(" #n ")" ::: "memory")
; #define PG8_BAR __builtin_amdgcn_s_barrier()
; #define PG8_SCHED __builtin_amdgcn_sched_barrier(0)
; template <class Epi, class Sched>
; __device__ __forceinline__ void gemm_phase(LAS unsigned char* lds, const Gemm g, const Sched& S, const Epi& E) {
;     ...
;             PG8_BAR; PG8_WAIT_L(0); PG8_MMA(1, 0, At, B0); PG8_BAR; PG8_SCHED;
;             PG8_STAGE(PG8_SB(1, 1), b3 + hstep, voffB);
;             PG8_WAIT_V(6); PG8_BAR; PG8_MMA(1, 1, At, B1); PG8_BAR;
;         }
	s_waitcnt lgkmcnt(0)
	s_setprio 1
	s_waitcnt lgkmcnt(0)
	v_mfma_f32_16x16x32_bf16 v[60:63], v[142:145], v[158:161], v[60:63]
	v_mfma_f32_16x16x32_bf16 v[52:55], v[142:145], v[166:169], v[52:55]
	v_mfma_f32_16x16x32_bf16 v[36:39], v[142:145], v[192:195], v[36:39]
	v_mfma_f32_16x16x32_bf16 v[20:23], v[142:145], v[200:203], v[20:23]
	v_mfma_f32_16x16x32_bf16 v[56:59], v[150:153], v[158:161], v[56:59]
	v_mfma_f32_16x16x32_bf16 v[48:51], v[150:153], v[166:169], v[48:51]
	v_mfma_f32_16x16x32_bf16 v[32:35], v[150:153], v[192:195], v[32:35]
	v_mfma_f32_16x16x32_bf16 v[16:19], v[150:153], v[200:203], v[16:19]
	v_mfma_f32_16x16x32_bf16 v[60:63], v[146:149], v[162:165], v[60:63]
	v_mfma_f32_16x16x32_bf16 v[52:55], v[146:149], v[170:173], v[52:55]
	v_mfma_f32_16x16x32_bf16 v[36:39], v[146:149], v[196:199], v[36:39]
	v_mfma_f32_16x16x32_bf16 v[20:23], v[146:149], v[204:207], v[20:23]
	v_mfma_f32_16x16x32_bf16 v[56:59], v[154:157], v[162:165], v[56:59]
	v_mfma_f32_16x16x32_bf16 v[48:51], v[154:157], v[170:173], v[48:51]
	v_mfma_f32_16x16x32_bf16 v[32:35], v[154:157], v[196:199], v[32:35]
	v_mfma_f32_16x16x32_bf16 v[16:19], v[154:157], v[204:207], v[16:19]
	s_setprio 0
	s_barrier
	s_add_u32 s18, s18, 0x80080
	s_addc_u32 s19, s19, 0
	s_add_i32 s20, s20, s23
	v_lshl_add_u64 v[142:143], s[18:19], 0, v[176:177]
	s_mov_b32 m0, s20
	s_nop 0
	global_load_lds_dwordx4 v[142:143], off
	v_lshl_add_u64 v[142:143], s[18:19], 0, v[128:129]
	s_add_i32 m0, s20, 0x2000
	s_nop 0
	global_load_lds_dwordx4 v[142:143], off
	s_waitcnt vmcnt(6)
	s_barrier
	s_setprio 1
	v_mfma_f32_16x16x32_bf16 v[44:47], v[208:211], v[158:161], v[44:47]
	v_mfma_f32_16x16x32_bf16 v[28:31], v[208:211], v[166:169], v[28:31]
	v_mfma_f32_16x16x32_bf16 v[12:15], v[208:211], v[192:195], v[12:15]
	v_mfma_f32_16x16x32_bf16 v[4:7], v[208:211], v[200:203], v[4:7]
	v_mfma_f32_16x16x32_bf16 v[40:43], v[216:219], v[158:161], v[40:43]
	v_mfma_f32_16x16x32_bf16 v[24:27], v[216:219], v[166:169], v[24:27]
	v_mfma_f32_16x16x32_bf16 v[8:11], v[216:219], v[192:195], v[8:11]
	v_mfma_f32_16x16x32_bf16 v[0:3], v[216:219], v[200:203], v[0:3]
	v_mfma_f32_16x16x32_bf16 v[44:47], v[212:215], v[162:165], v[44:47]
	v_mfma_f32_16x16x32_bf16 v[28:31], v[212:215], v[170:173], v[28:31]
	v_mfma_f32_16x16x32_bf16 v[12:15], v[212:215], v[196:199], v[12:15]
	v_mfma_f32_16x16x32_bf16 v[4:7], v[212:215], v[204:207], v[4:7]
	v_mfma_f32_16x16x32_bf16 v[40:43], v[220:223], v[162:165], v[40:43]
	v_mfma_f32_16x16x32_bf16 v[24:27], v[220:223], v[170:173], v[24:27]
	v_mfma_f32_16x16x32_bf16 v[8:11], v[220:223], v[196:199], v[8:11]
	v_mfma_f32_16x16x32_bf16 v[0:3], v[220:223], v[204:207], v[0:3]
	s_setprio 0
	s_add_i32 s38, s38, 2
	s_add_u32 s36, s36, 0x100
	s_addc_u32 s37, s37, 0
	s_add_u32 s16, s16, 0x100
	s_addc_u32 s17, s17, 0
	s_cmp_gt_u32 s38, 29
	s_barrier
	s_cbranch_scc0 .LBB0_852
; __device__ __forceinline__ unsigned cvt_pk_bf16(float lo, float hi) { return pk2(lo, hi); }
; #define PG8_WAIT_V(n) asm volatile("s_waitcnt vmcnt(" #n ")" ::: "memory")
; #define PG8_BAR __builtin_amdgcn_s_barrier()
;     __device__ __forceinline__ void operator()(const f32x4 (&acc)[2][2][4][2], const Unit& u, int wr, int wc, int fr, int fq) const {
;         const int row0 = u.pm * BM + wr * 64 + fr, col0 = u.pn * BM + wc * 32 + 8 * fq;
; #pragma unroll
;         for (int ai = 0; ai < 2; ++ai)
; #pragma unroll
;             for (int m = 0; m < 4; ++m) { bf16_t* rowp = O + (size_t)(row0 + ai * HALF + m * 16) * ldc + col0;
; #pragma unroll
;                 for (int bj = 0; bj < 2; ++bj) { f32x4 v0 = acc[ai][bj][m][0], v1 = acc[ai][bj][m][1];
;                     if (ACT == 1) {
; #pragma unroll
;                         for (int j = 0; j < 4; ++j) { float a = fmaxf(v0[j], 0.f), b = fmaxf(v1[j], 0.f); v0[j] = a * a; v1[j] = b * b; } }
;                     u32x4 w; w.x = cvt_pk_bf16(v0[0], v0[1]); w.y = cvt_pk_bf16(v0[2], v0[3]); w.z = cvt_pk_bf16(v1[0], v1[1]); w.w = cvt_pk_bf16(v1[2], v1[3]);
;                     *(u32x4*)(rowp + bj * HALF) = w; } }
; template <class Epi, class Sched>
; __device__ __forceinline__ void gemm_phase(LAS unsigned char* lds, const Gemm g, const Sched& S, const Epi& E) {
;     ...
;         if constexpr (!Epi::AFTER_DRAIN) E(acc, cur, wr, wc, fr, fq);
;         if (!has_next) break;
; #pragma unroll
;         for (int a = 0; a < 2; ++a)
; #pragma unroll
;             for (int b = 0; b < 2; ++b)
; #pragma unroll
;                 for (int m = 0; m < 4; ++m)
; #pragma unroll
;                     for (int n = 0; n < 2; ++n) acc[a][b][m][n] = (f32x4){0.f, 0.f, 0.f, 0.f};
;         cur = nxt; cA = nA; cB = nB; ++ui;
;     }
;     PG8_WAIT_V(0);
;     if (wr == 0) PG8_BAR;
;     PG8_BAR;
	v_lshl_add_u32 v148, s6, 8, v138
	v_lshl_or_b32 v142, s33, 8, v140
	v_ashrrev_i32_e32 v143, 31, v142
	v_mov_b64_e32 v[144:145], s[0:1]
	v_cvt_pk_bf16_f32 v68, v68, v69
	v_cvt_pk_bf16_f32 v69, v70, v71
	v_cvt_pk_bf16_f32 v70, v64, v65
	v_add_u32_e32 v64, 0x80, v148
	v_mad_i64_i32 v[146:147], s[16:17], v148, s78, v[144:145]
	v_lshlrev_b64 v[142:143], 1, v[142:143]
	v_cvt_pk_bf16_f32 v108, v108, v109
	v_cvt_pk_bf16_f32 v109, v110, v111
	v_cvt_pk_bf16_f32 v110, v104, v105
	v_or_b32_e32 v104, 16, v148
	v_mad_i64_i32 v[64:65], s[16:17], v64, s78, v[144:145]
	v_cvt_pk_bf16_f32 v44, v44, v45
	v_cvt_pk_bf16_f32 v45, v46, v47
	v_cvt_pk_bf16_f32 v46, v40, v41
	v_add_u32_e32 v40, 0x90, v148
	v_lshl_add_u64 v[146:147], v[146:147], 0, v[142:143]
	v_cvt_pk_bf16_f32 v111, v106, v107
	v_mad_i64_i32 v[104:105], s[16:17], v104, s78, v[144:145]
	v_cvt_pk_bf16_f32 v92, v92, v93
	v_cvt_pk_bf16_f32 v93, v94, v95
	v_cvt_pk_bf16_f32 v94, v88, v89
	v_or_b32_e32 v88, 32, v148
	v_lshl_add_u64 v[64:65], v[64:65], 0, v[142:143]
	v_cvt_pk_bf16_f32 v47, v42, v43
	v_mad_i64_i32 v[40:41], s[16:17], v40, s78, v[144:145]
	v_cvt_pk_bf16_f32 v28, v28, v29
	v_cvt_pk_bf16_f32 v29, v30, v31
	v_cvt_pk_bf16_f32 v30, v24, v25
	v_add_u32_e32 v24, 0xa0, v148
	global_store_dwordx4 v[146:147], v[108:111], off offset:256
	v_cvt_pk_bf16_f32 v95, v90, v91
	v_mad_i64_i32 v[88:89], s[16:17], v88, s78, v[144:145]
	v_lshl_add_u64 v[108:109], v[104:105], 0, v[142:143]
	v_cvt_pk_bf16_f32 v76, v76, v77
	v_cvt_pk_bf16_f32 v77, v78, v79
	v_cvt_pk_bf16_f32 v78, v72, v73
	v_or_b32_e32 v72, 48, v148
	global_store_dwordx4 v[64:65], v[44:47], off offset:256
	v_cvt_pk_bf16_f32 v31, v26, v27
	v_mad_i64_i32 v[24:25], s[16:17], v24, s78, v[144:145]
	v_lshl_add_u64 v[44:45], v[40:41], 0, v[142:143]
	v_cvt_pk_bf16_f32 v12, v12, v13
	v_cvt_pk_bf16_f32 v13, v14, v15
	v_cvt_pk_bf16_f32 v14, v8, v9
	v_add_u32_e32 v8, 0xb0, v148
	global_store_dwordx4 v[108:109], v[92:95], off offset:256
	v_cvt_pk_bf16_f32 v79, v74, v75
	v_mad_i64_i32 v[72:73], s[16:17], v72, s78, v[144:145]
	v_lshl_add_u64 v[92:93], v[88:89], 0, v[142:143]
	global_store_dwordx4 v[44:45], v[28:31], off offset:256
	v_cvt_pk_bf16_f32 v15, v10, v11
	v_mad_i64_i32 v[8:9], s[16:17], v8, s78, v[144:145]
	v_lshl_add_u64 v[28:29], v[24:25], 0, v[142:143]
	v_cvt_pk_bf16_f32 v124, v124, v125
	v_cvt_pk_bf16_f32 v125, v126, v127
	v_cvt_pk_bf16_f32 v126, v120, v121
	v_cvt_pk_bf16_f32 v127, v122, v123
	v_cvt_pk_bf16_f32 v104, v116, v117
	v_cvt_pk_bf16_f32 v105, v118, v119
	v_cvt_pk_bf16_f32 v106, v112, v113
	v_cvt_pk_bf16_f32 v107, v114, v115
	v_cvt_pk_bf16_f32 v88, v100, v101
	v_cvt_pk_bf16_f32 v89, v102, v103
	v_cvt_pk_bf16_f32 v90, v96, v97
	v_cvt_pk_bf16_f32 v91, v98, v99
	global_store_dwordx4 v[92:93], v[76:79], off offset:256
	v_cvt_pk_bf16_f32 v74, v80, v81
	v_cvt_pk_bf16_f32 v75, v82, v83
	v_lshl_add_u64 v[76:77], v[72:73], 0, v[142:143]
	v_cvt_pk_bf16_f32 v72, v84, v85
	v_cvt_pk_bf16_f32 v73, v86, v87
	v_cvt_pk_bf16_f32 v71, v66, v67
	v_cvt_pk_bf16_f32 v60, v60, v61
	v_cvt_pk_bf16_f32 v61, v62, v63
	v_cvt_pk_bf16_f32 v62, v56, v57
	v_cvt_pk_bf16_f32 v63, v58, v59
	v_cvt_pk_bf16_f32 v40, v52, v53
	v_cvt_pk_bf16_f32 v41, v54, v55
	v_cvt_pk_bf16_f32 v42, v48, v49
	v_cvt_pk_bf16_f32 v43, v50, v51
	v_cvt_pk_bf16_f32 v24, v36, v37
	v_cvt_pk_bf16_f32 v25, v38, v39
	v_cvt_pk_bf16_f32 v26, v32, v33
	v_cvt_pk_bf16_f32 v27, v34, v35
	global_store_dwordx4 v[28:29], v[12:15], off offset:256
	v_cvt_pk_bf16_f32 v10, v16, v17
	v_cvt_pk_bf16_f32 v11, v18, v19
	v_lshl_add_u64 v[12:13], v[8:9], 0, v[142:143]
	v_cvt_pk_bf16_f32 v8, v20, v21
	v_cvt_pk_bf16_f32 v9, v22, v23
	v_cvt_pk_bf16_f32 v4, v4, v5
	v_cvt_pk_bf16_f32 v5, v6, v7
	v_cvt_pk_bf16_f32 v6, v0, v1
	v_cvt_pk_bf16_f32 v7, v2, v3
	s_and_b64 vcc, exec, s[4:5]
	s_mov_b32 s33, s8
	s_mov_b32 s6, s10
	s_mov_b64 s[16:17], s[14:15]
	s_mov_b64 s[18:19], s[12:13]
	global_store_dwordx4 v[146:147], v[124:127], off
	global_store_dwordx4 v[108:109], v[104:107], off
	global_store_dwordx4 v[92:93], v[88:91], off
	global_store_dwordx4 v[76:77], v[72:75], off
	global_store_dwordx4 v[76:77], v[68:71], off offset:256
	global_store_dwordx4 v[64:65], v[60:63], off
	global_store_dwordx4 v[44:45], v[40:43], off
	global_store_dwordx4 v[28:29], v[24:27], off
	global_store_dwordx4 v[12:13], v[8:11], off
	global_store_dwordx4 v[12:13], v[4:7], off offset:256
	s_cbranch_vccz .LBB0_849
	s_waitcnt vmcnt(0)
	s_cmpk_gt_u32 s2, 0xff
	s_mov_b32 s29, s45
	s_mov_b32 s30, s46
	s_mov_b32 s33, 0x10000
	s_cbranch_scc1 .LBB0_856
	s_barrier
